# accumulator zeroing interleaved with the scalar next-tile arithmetic (two waves of a SIMD overlap SALU chain and VALU); no-next path zeroes from an out-of-line copy
# baseline (speedup 1.0000x reference)
; template <class Epi, class Sched, bool ALIGN_EPI = false, bool SP2 = false>
; __device__ __forceinline__ void gemm_phase(PG8_LAS unsigned char* lds, const Gemm g, const Sched& S, const Epi& E, const int tid) {
;     ...
; #pragma unroll
;         for (int a = 0; a < 2; ++a)
; #pragma unroll
;             for (int b = 0; b < 2; ++b)
; #pragma unroll
;                 for (int m = 0; m < 4; ++m)
; #pragma unroll
;                     for (int n = 0; n < 2; ++n) acc[a][b][m][n] = (f32x4){0.f, 0.f, 0.f, 0.f};
;         cur = nxt; cA = nA; cB = nB; ++ui;
.Lzfix_0:
	v_mov_b64_e32 v[2:3], 0
	v_mov_b64_e32 v[4:5], 0
	v_mov_b64_e32 v[6:7], 0
	v_mov_b64_e32 v[8:9], 0
	v_mov_b64_e32 v[10:11], 0
	v_mov_b64_e32 v[12:13], 0
	v_mov_b64_e32 v[14:15], 0
	v_mov_b64_e32 v[16:17], 0
	v_mov_b64_e32 v[18:19], 0
	v_mov_b64_e32 v[20:21], 0
	v_mov_b64_e32 v[22:23], 0
	v_mov_b64_e32 v[24:25], 0
	v_mov_b64_e32 v[26:27], 0
	v_mov_b64_e32 v[28:29], 0
	v_mov_b64_e32 v[30:31], 0
	v_mov_b64_e32 v[32:33], 0
	v_mov_b64_e32 v[34:35], 0
	v_mov_b64_e32 v[36:37], 0
	v_mov_b64_e32 v[38:39], 0
	v_mov_b64_e32 v[40:41], 0
	v_mov_b64_e32 v[42:43], 0
	v_mov_b64_e32 v[44:45], 0
	v_mov_b64_e32 v[46:47], 0
	v_mov_b64_e32 v[48:49], 0
	v_mov_b64_e32 v[50:51], 0
	v_mov_b64_e32 v[52:53], 0
	v_mov_b64_e32 v[54:55], 0
	v_mov_b64_e32 v[56:57], 0
	v_mov_b64_e32 v[58:59], 0
	v_mov_b64_e32 v[60:61], 0
	v_mov_b64_e32 v[62:63], 0
	v_mov_b64_e32 v[64:65], 0
	v_mov_b64_e32 v[66:67], 0
	v_mov_b64_e32 v[68:69], 0
	v_mov_b64_e32 v[70:71], 0
	v_mov_b64_e32 v[72:73], 0
	v_mov_b64_e32 v[74:75], 0
	v_mov_b64_e32 v[76:77], 0
	v_mov_b64_e32 v[78:79], 0
	v_mov_b64_e32 v[80:81], 0
	v_mov_b64_e32 v[82:83], 0
	s_branch .LBB0_549

;     __host__ __device__ bool next(int i, Unit& u) const {
;         const long L = (long)i * G + c; if (L >= nwg) return false;
;         int wgid = (int)L; { const int q = nwg / NXCD, r = nwg % NXCD, xcd = wgid % NXCD, off = wgid / NXCD; wgid = (xcd < r ? xcd * (q + 1) : r * (q + 1) + (xcd - r) * q) + off; }
;         const int nig = WGM * nN, gid = wgid / nig, fm = gid * WGM, gsz = (nM - fm) < WGM ? (nM - fm) : WGM;
;         u.pm = fm + ((wgid % nig) % gsz); u.pn = (wgid % nig) / gsz; return true;
; template <class Epi, class Sched, bool ALIGN_EPI = false, bool SP2 = false>
; __device__ __forceinline__ void gemm_phase(PG8_LAS unsigned char* lds, const Gemm g, const Sched& S, const Epi& E, const int tid) {
;     ...
; #pragma unroll
;         for (int a = 0; a < 2; ++a)
; #pragma unroll
;             for (int b = 0; b < 2; ++b)
; #pragma unroll
;                 for (int m = 0; m < 4; ++m)
; #pragma unroll
;                     for (int n = 0; n < 2; ++n) acc[a][b][m][n] = (f32x4){0.f, 0.f, 0.f, 0.f};
;         cur = nxt; cA = nA; cB = nB; ++ui;
.LBB0_548:
	s_ashr_i32 s7, s7, 3
	v_mov_b64_e32 v[2:3], 0
	s_add_i32 s7, s59, s7
	v_mov_b64_e32 v[4:5], 0
	s_mul_hi_i32 s34, s7, 0x2e8ba2e9
	v_mov_b64_e32 v[6:7], 0
	s_lshr_b32 s35, s34, 31
	v_mov_b64_e32 v[8:9], 0
	s_ashr_i32 s34, s34, 5
	v_mov_b64_e32 v[10:11], 0
	s_add_i32 s34, s34, s35
	v_mov_b64_e32 v[12:13], 0
	s_lshl_b32 s35, s34, 3
	v_mov_b64_e32 v[14:15], 0
	s_sub_i32 s58, 0x42, s35
	v_mov_b64_e32 v[16:17], 0
	s_min_i32 s58, s58, 8
	v_mov_b64_e32 v[18:19], 0
	s_abs_i32 s59, s58
	v_mov_b64_e32 v[20:21], 0
	v_cvt_f32_u32_e32 v0, s59
	v_mov_b64_e32 v[22:23], 0
	s_sub_i32 s78, 0, s59
	v_mov_b64_e32 v[24:25], 0
	s_mulk_i32 s34, 0xb0
	v_mov_b64_e32 v[26:27], 0
	s_sub_i32 s7, s7, s34
	v_mov_b64_e32 v[28:29], 0
	v_rcp_iflag_f32_e32 v0, v0
	v_mov_b64_e32 v[30:31], 0
	s_abs_i32 s34, s7
	v_mov_b64_e32 v[32:33], 0
	s_xor_b32 s73, s7, s58
	v_mov_b64_e32 v[34:35], 0
	s_ashr_i32 s73, s73, 31
	v_mov_b64_e32 v[36:37], 0
	v_mul_f32_e32 v0, 0x4f7ffffe, v0
	v_mov_b64_e32 v[38:39], 0
	v_cvt_u32_f32_e32 v0, v0
	v_mov_b64_e32 v[40:41], 0
	s_mov_b64 s[90:91], -1
	v_mov_b64_e32 v[42:43], 0
	v_readfirstlane_b32 s79, v0
	v_mov_b64_e32 v[44:45], 0
	s_mul_i32 s78, s78, s79
	v_mov_b64_e32 v[46:47], 0
	s_mul_hi_u32 s78, s79, s78
	v_mov_b64_e32 v[48:49], 0
	s_add_i32 s79, s79, s78
	v_mov_b64_e32 v[50:51], 0
	s_mul_hi_u32 s78, s34, s79
	v_mov_b64_e32 v[52:53], 0
	s_mul_i32 s79, s78, s59
	v_mov_b64_e32 v[54:55], 0
	s_sub_i32 s34, s34, s79
	v_mov_b64_e32 v[56:57], 0
	s_add_i32 s86, s78, 1
	v_mov_b64_e32 v[58:59], 0
	s_sub_i32 s79, s34, s59
	v_mov_b64_e32 v[60:61], 0
	s_cmp_ge_u32 s34, s59
	v_mov_b64_e32 v[62:63], 0
	s_cselect_b32 s78, s86, s78
	v_mov_b64_e32 v[64:65], 0
	s_cselect_b32 s34, s79, s34
	v_mov_b64_e32 v[66:67], 0
	s_add_i32 s79, s78, 1
	v_mov_b64_e32 v[68:69], 0
	s_cmp_ge_u32 s34, s59
	v_mov_b64_e32 v[70:71], 0
	s_cselect_b32 s34, s79, s78
	v_mov_b64_e32 v[72:73], 0
	s_xor_b32 s34, s34, s73
	v_mov_b64_e32 v[74:75], 0
	s_sub_i32 s86, s34, s73
	v_mov_b64_e32 v[76:77], 0
	s_mul_i32 s34, s86, s58
	v_mov_b64_e32 v[78:79], 0
	s_sub_i32 s7, s7, s34
	v_mov_b64_e32 v[80:81], 0
	s_add_i32 s88, s35, s7
	v_mov_b64_e32 v[82:83], 0
.LBB0_549:
	s_ashr_i32 s89, s88, 31
	v_mov_b64_e32 v[84:85], 0
	s_lshl_b64 s[34:35], s[88:89], 19
	v_mov_b64_e32 v[86:87], 0
	s_add_u32 s92, s1, s34
	v_mov_b64_e32 v[88:89], 0
	s_addc_u32 s93, s3, s35
	v_mov_b64_e32 v[90:91], 0
	s_and_b64 s[34:35], s[90:91], exec
	v_mov_b64_e32 v[124:125], 0
	s_cselect_b32 s7, s93, s23
	v_mov_b64_e32 v[126:127], 0
	s_cselect_b32 s58, s92, s22
	v_mov_b64_e32 v[128:129], 0
	s_ashr_i32 s87, s86, 31
	v_mov_b64_e32 v[130:131], 0
	s_lshl_b64 s[34:35], s[86:87], 19
	v_mov_b64_e32 v[132:133], 0
	s_add_u32 s94, s4, s34
	v_mov_b64_e32 v[134:135], 0
	s_addc_u32 s95, s5, s35
	v_mov_b64_e32 v[136:137], 0
	s_and_b64 s[34:35], s[90:91], exec
	v_mov_b64_e32 v[138:139], 0
	s_cselect_b32 s59, s95, s11
	v_mov_b64_e32 v[140:141], 0
	s_cselect_b32 s73, s94, s10
	v_mov_b64_e32 v[142:143], 0
	s_add_u32 s78, s10, 0x100
	v_mov_b64_e32 v[144:145], 0
	s_addc_u32 s79, s11, 0
	v_mov_b64_e32 v[146:147], 0
	s_add_u32 s10, s22, 0x40080
	v_mov_b64_e32 v[148:149], 0
	s_addc_u32 s11, s23, 0
	v_mov_b64_e32 v[150:151], 0
	s_mov_b32 s87, -2
	v_mov_b64_e32 v[152:153], 0
	v_mov_b64_e32 v[154:155], 0
	v_mov_b64_e32 v[156:157], 0
	v_mov_b64_e32 v[158:159], 0
	v_mov_b64_e32 v[0:1], 0

;     __host__ __device__ bool next(int i, Unit& u) const {
;         const long L = (long)i * G + c; if (L >= nwg) return false;
;         int wgid = (int)L; { const int q = nwg / NXCD, r = nwg % NXCD, xcd = wgid % NXCD, off = wgid / NXCD; wgid = (xcd < r ? xcd * (q + 1) : r * (q + 1) + (xcd - r) * q) + off; }
;         const int nig = WGM * nN, gid = wgid / nig, fm = gid * WGM, gsz = (nM - fm) < WGM ? (nM - fm) : WGM;
;         u.pm = fm + ((wgid % nig) % gsz); u.pn = (wgid % nig) / gsz; return true;
; template <class Epi, class Sched, bool ALIGN_EPI = false, bool SP2 = false>
; __device__ __forceinline__ void gemm_phase(PG8_LAS unsigned char* lds, const Gemm g, const Sched& S, const Epi& E, const int tid) {
;     ...
; #pragma unroll
;         for (int a = 0; a < 2; ++a)
; #pragma unroll
;             for (int b = 0; b < 2; ++b)
; #pragma unroll
;                 for (int m = 0; m < 4; ++m)
; #pragma unroll
;                     for (int n = 0; n < 2; ++n) acc[a][b][m][n] = (f32x4){0.f, 0.f, 0.f, 0.f};
;         cur = nxt; cA = nA; cB = nB; ++ui;
.LBB0_1244:
	s_ashr_i32 s40, s42, 3
	v_mov_b64_e32 v[2:3], 0
	s_add_i32 s40, s44, s40
	v_mov_b64_e32 v[4:5], 0
	s_ashr_i32 s41, s40, 31
	v_mov_b64_e32 v[6:7], 0
	s_lshr_b32 s41, s41, 25
	v_mov_b64_e32 v[8:9], 0
	s_add_i32 s41, s40, s41
	v_mov_b64_e32 v[10:11], 0
	s_ashr_i32 s42, s41, 7
	v_mov_b64_e32 v[12:13], 0
	s_lshl_b32 s42, s42, 3
	v_mov_b64_e32 v[14:15], 0
	s_sub_i32 s43, 64, s42
	v_mov_b64_e32 v[16:17], 0
	s_min_i32 s43, s43, 8
	v_mov_b64_e32 v[18:19], 0
	s_abs_i32 s44, s43
	v_mov_b64_e32 v[20:21], 0
	v_cvt_f32_u32_e32 v0, s44
	v_mov_b64_e32 v[22:23], 0
	s_sub_i32 s46, 0, s44
	v_mov_b64_e32 v[24:25], 0
	s_and_b32 s41, s41, 0xffffff80
	v_mov_b64_e32 v[26:27], 0
	s_sub_i32 s41, s40, s41
	v_mov_b64_e32 v[28:29], 0
	v_rcp_iflag_f32_e32 v0, v0
	v_mov_b64_e32 v[30:31], 0
	s_abs_i32 s40, s41
	v_mov_b64_e32 v[32:33], 0
	s_xor_b32 s45, s41, s43
	v_mov_b64_e32 v[34:35], 0
	s_ashr_i32 s45, s45, 31
	v_mov_b64_e32 v[36:37], 0
	v_mul_f32_e32 v0, 0x4f7ffffe, v0
	v_mov_b64_e32 v[38:39], 0
	v_cvt_u32_f32_e32 v0, v0
	v_mov_b64_e32 v[40:41], 0
	s_nop 0
	v_mov_b64_e32 v[42:43], 0
	v_readfirstlane_b32 s47, v0
	v_mov_b64_e32 v[44:45], 0
	s_mul_i32 s46, s46, s47
	v_mov_b64_e32 v[46:47], 0
	s_mul_hi_u32 s46, s47, s46
	v_mov_b64_e32 v[48:49], 0
	s_add_i32 s47, s47, s46
	v_mov_b64_e32 v[50:51], 0
	s_mul_hi_u32 s46, s40, s47
	v_mov_b64_e32 v[52:53], 0
	s_mul_i32 s47, s46, s44
	v_mov_b64_e32 v[54:55], 0
	s_sub_i32 s40, s40, s47
	v_mov_b64_e32 v[56:57], 0
	s_add_i32 s50, s46, 1
	v_mov_b64_e32 v[58:59], 0
	s_sub_i32 s47, s40, s44
	v_mov_b64_e32 v[60:61], 0
	s_cmp_ge_u32 s40, s44
	v_mov_b64_e32 v[62:63], 0
	s_cselect_b32 s46, s50, s46
	v_mov_b64_e32 v[64:65], 0
	s_cselect_b32 s40, s47, s40
	v_mov_b64_e32 v[66:67], 0
	s_add_i32 s47, s46, 1
	v_mov_b64_e32 v[68:69], 0
	s_cmp_ge_u32 s40, s44
	v_mov_b64_e32 v[70:71], 0
	s_cselect_b32 s40, s47, s46
	v_mov_b64_e32 v[72:73], 0
	s_xor_b32 s40, s40, s45
	v_mov_b64_e32 v[74:75], 0
	s_sub_i32 s40, s40, s45
	v_mov_b64_e32 v[76:77], 0
	s_mul_i32 s43, s40, s43
	v_mov_b64_e32 v[78:79], 0
	s_sub_i32 s41, s41, s43
	v_mov_b64_e32 v[80:81], 0
	s_add_i32 s42, s42, s41
	v_mov_b64_e32 v[82:83], 0
.LBB0_1245:
	s_ashr_i32 s43, s42, 31
	v_mov_b64_e32 v[84:85], 0
	s_lshl_b64 s[44:45], s[42:43], 19
	v_mov_b64_e32 v[86:87], 0
	s_add_u32 s44, s3, s44
	v_mov_b64_e32 v[88:89], 0
	s_addc_u32 s45, s4, s45
	v_mov_b64_e32 v[90:91], 0
	s_and_b64 s[46:47], s[12:13], exec
	v_mov_b64_e32 v[92:93], 0
	s_cselect_b32 s43, s45, s7
	v_mov_b64_e32 v[94:95], 0
	s_cselect_b32 s58, s44, s6
	v_mov_b64_e32 v[96:97], 0
	s_ashr_i32 s41, s40, 31
	v_mov_b64_e32 v[98:99], 0
	s_lshl_b64 s[46:47], s[40:41], 19
	v_mov_b64_e32 v[100:101], 0
	s_add_u32 s46, s5, s46
	v_mov_b64_e32 v[102:103], 0
	s_addc_u32 s47, s33, s47
	v_mov_b64_e32 v[104:105], 0
	s_and_b64 s[50:51], s[12:13], exec
	v_mov_b64_e32 v[106:107], 0
	s_cselect_b32 s41, s47, s49
	v_mov_b64_e32 v[108:109], 0
	s_cselect_b32 s59, s46, s48
	v_mov_b64_e32 v[110:111], 0
	s_add_u32 s6, s6, 0x40080
	v_mov_b64_e32 v[112:113], 0
	s_addc_u32 s7, s7, 0
	v_mov_b64_e32 v[114:115], 0
	s_add_u32 s72, s48, 0x100
	v_mov_b64_e32 v[116:117], 0
	s_addc_u32 s73, s49, 0
	v_mov_b64_e32 v[118:119], 0
	s_mov_b32 s74, -2
	v_mov_b64_e32 v[120:121], 0
	v_mov_b64_e32 v[122:123], 0
	v_mov_b64_e32 v[124:125], 0
	v_mov_b64_e32 v[126:127], 0
	v_mov_b64_e32 v[0:1], 0

;     __host__ __device__ bool next(int i, Unit& u) const {
;         const long L = (long)i * G + c; if (L >= nwg) return false;
;         int wgid = (int)L; { const int q = nwg / NXCD, r = nwg % NXCD, xcd = wgid % NXCD, off = wgid / NXCD; wgid = (xcd < r ? xcd * (q + 1) : r * (q + 1) + (xcd - r) * q) + off; }
;         const int nig = WGM * nN, gid = wgid / nig, fm = gid * WGM, gsz = (nM - fm) < WGM ? (nM - fm) : WGM;
;         u.pm = fm + ((wgid % nig) % gsz); u.pn = (wgid % nig) / gsz; return true;
; template <class Epi, class Sched, bool ALIGN_EPI = false, bool SP2 = false>
; __device__ __forceinline__ void gemm_phase(PG8_LAS unsigned char* lds, const Gemm g, const Sched& S, const Epi& E, const int tid) {
;     ...
; #pragma unroll
;         for (int a = 0; a < 2; ++a)
; #pragma unroll
;             for (int b = 0; b < 2; ++b)
; #pragma unroll
;                 for (int m = 0; m < 4; ++m)
; #pragma unroll
;                     for (int n = 0; n < 2; ++n) acc[a][b][m][n] = (f32x4){0.f, 0.f, 0.f, 0.f};
;         cur = nxt; cA = nA; cB = nB; ++ui;
.LBB0_1515:
	s_ashr_i32 s26, s28, 3
	v_mov_b64_e32 v[2:3], 0
	s_add_i32 s26, s30, s26
	v_mov_b64_e32 v[4:5], 0
	s_ashr_i32 s27, s26, 31
	v_mov_b64_e32 v[6:7], 0
	s_lshr_b32 s27, s27, 27
	v_mov_b64_e32 v[8:9], 0
	s_add_i32 s27, s26, s27
	v_mov_b64_e32 v[10:11], 0
	s_ashr_i32 s28, s27, 5
	v_mov_b64_e32 v[12:13], 0
	s_lshl_b32 s28, s28, 3
	v_mov_b64_e32 v[14:15], 0
	s_sub_i32 s29, 64, s28
	v_mov_b64_e32 v[16:17], 0
	s_min_i32 s29, s29, 8
	v_mov_b64_e32 v[18:19], 0
	s_abs_i32 s30, s29
	v_mov_b64_e32 v[20:21], 0
	v_cvt_f32_u32_e32 v0, s30
	v_mov_b64_e32 v[22:23], 0
	s_sub_i32 s34, 0, s30
	v_mov_b64_e32 v[24:25], 0
	s_andn2_b32 s27, s27, 31
	v_mov_b64_e32 v[26:27], 0
	s_sub_i32 s27, s26, s27
	v_mov_b64_e32 v[28:29], 0
	v_rcp_iflag_f32_e32 v0, v0
	v_mov_b64_e32 v[30:31], 0
	s_abs_i32 s26, s27
	v_mov_b64_e32 v[32:33], 0
	s_xor_b32 s31, s27, s29
	v_mov_b64_e32 v[34:35], 0
	s_ashr_i32 s31, s31, 31
	v_mov_b64_e32 v[36:37], 0
	v_mul_f32_e32 v0, 0x4f7ffffe, v0
	v_mov_b64_e32 v[38:39], 0
	v_cvt_u32_f32_e32 v0, v0
	v_mov_b64_e32 v[40:41], 0
	s_nop 0
	v_mov_b64_e32 v[42:43], 0
	v_readfirstlane_b32 s35, v0
	v_mov_b64_e32 v[44:45], 0
	s_mul_i32 s34, s34, s35
	v_mov_b64_e32 v[46:47], 0
	s_mul_hi_u32 s34, s35, s34
	v_mov_b64_e32 v[48:49], 0
	s_add_i32 s35, s35, s34
	v_mov_b64_e32 v[50:51], 0
	s_mul_hi_u32 s34, s26, s35
	v_mov_b64_e32 v[52:53], 0
	s_mul_i32 s35, s34, s30
	v_mov_b64_e32 v[54:55], 0
	s_sub_i32 s26, s26, s35
	v_mov_b64_e32 v[56:57], 0
	s_add_i32 s40, s34, 1
	v_mov_b64_e32 v[58:59], 0
	s_sub_i32 s35, s26, s30
	v_mov_b64_e32 v[60:61], 0
	s_cmp_ge_u32 s26, s30
	v_mov_b64_e32 v[62:63], 0
	s_cselect_b32 s34, s40, s34
	v_mov_b64_e32 v[64:65], 0
	s_cselect_b32 s26, s35, s26
	v_mov_b64_e32 v[66:67], 0
	s_add_i32 s35, s34, 1
	v_mov_b64_e32 v[68:69], 0
	s_cmp_ge_u32 s26, s30
	v_mov_b64_e32 v[70:71], 0
	s_cselect_b32 s26, s35, s34
	v_mov_b64_e32 v[72:73], 0
	s_xor_b32 s26, s26, s31
	v_mov_b64_e32 v[74:75], 0
	s_sub_i32 s26, s26, s31
	v_mov_b64_e32 v[76:77], 0
	s_mul_i32 s29, s26, s29
	v_mov_b64_e32 v[78:79], 0
	s_sub_i32 s27, s27, s29
	v_mov_b64_e32 v[80:81], 0
	s_add_i32 s28, s28, s27
	v_mov_b64_e32 v[82:83], 0
.LBB0_1516:
	s_ashr_i32 s29, s28, 31
	v_mov_b64_e32 v[84:85], 0
	s_lshl_b64 s[30:31], s[28:29], 19
	v_mov_b64_e32 v[86:87], 0
	s_add_u32 s30, s3, s30
	v_mov_b64_e32 v[88:89], 0
	s_addc_u32 s31, s4, s31
	v_mov_b64_e32 v[90:91], 0
	s_and_b64 s[34:35], s[12:13], exec
	v_mov_b64_e32 v[92:93], 0
	s_cselect_b32 s29, s31, s37
	v_mov_b64_e32 v[94:95], 0
	s_cselect_b32 s60, s30, s36
	v_mov_b64_e32 v[96:97], 0
	s_ashr_i32 s27, s26, 31
	v_mov_b64_e32 v[98:99], 0
	s_lshl_b64 s[34:35], s[26:27], 19
	v_mov_b64_e32 v[100:101], 0
	s_add_u32 s34, s5, s34
	v_mov_b64_e32 v[102:103], 0
	s_addc_u32 s35, s33, s35
	v_mov_b64_e32 v[104:105], 0
	s_and_b64 s[40:41], s[12:13], exec
	v_mov_b64_e32 v[106:107], 0
	s_cselect_b32 s27, s35, s39
	v_mov_b64_e32 v[108:109], 0
	s_cselect_b32 s61, s34, s38
	v_mov_b64_e32 v[110:111], 0
	s_add_u32 s36, s36, 0x40080
	v_mov_b64_e32 v[112:113], 0
	s_addc_u32 s37, s37, 0
	v_mov_b64_e32 v[114:115], 0
	s_add_u32 s62, s38, 0x100
	v_mov_b64_e32 v[116:117], 0
	s_addc_u32 s63, s39, 0
	v_mov_b64_e32 v[118:119], 0
	s_mov_b32 s64, -2
	v_mov_b64_e32 v[120:121], 0
	v_mov_b64_e32 v[122:123], 0
	v_mov_b64_e32 v[124:125], 0
	v_mov_b64_e32 v[126:127], 0
	v_mov_b64_e32 v[0:1], 0

;     __host__ __device__ bool next(int i, Unit& u) const {
;         const long L = (long)i * G + c; if (L >= nwg) return false;
;         int wgid = (int)L; { const int q = nwg / NXCD, r = nwg % NXCD, xcd = wgid % NXCD, off = wgid / NXCD; wgid = (xcd < r ? xcd * (q + 1) : r * (q + 1) + (xcd - r) * q) + off; }
;         const int nig = WGM * nN, gid = wgid / nig, fm = gid * WGM, gsz = (nM - fm) < WGM ? (nM - fm) : WGM;
;         u.pm = fm + ((wgid % nig) % gsz); u.pn = (wgid % nig) / gsz; return true;
; template <class Epi, class Sched, bool ALIGN_EPI = false, bool SP2 = false>
; __device__ __forceinline__ void gemm_phase(PG8_LAS unsigned char* lds, const Gemm g, const Sched& S, const Epi& E, const int tid) {
;     ...
; #pragma unroll
;         for (int a = 0; a < 2; ++a)
; #pragma unroll
;             for (int b = 0; b < 2; ++b)
; #pragma unroll
;                 for (int m = 0; m < 4; ++m)
; #pragma unroll
;                     for (int n = 0; n < 2; ++n) acc[a][b][m][n] = (f32x4){0.f, 0.f, 0.f, 0.f};
;         cur = nxt; cA = nA; cB = nB; ++ui;
.LBB0_1666:
	s_ashr_i32 s7, s7, 3
	v_mov_b64_e32 v[2:3], 0
	s_add_i32 s7, s63, s7
	v_mov_b64_e32 v[4:5], 0
	s_mul_hi_i32 s58, s7, 0x2e8ba2e9
	v_mov_b64_e32 v[6:7], 0
	s_lshr_b32 s59, s58, 31
	v_mov_b64_e32 v[8:9], 0
	s_ashr_i32 s58, s58, 5
	v_mov_b64_e32 v[10:11], 0
	s_add_i32 s58, s58, s59
	v_mov_b64_e32 v[12:13], 0
	s_lshl_b32 s59, s58, 3
	v_mov_b64_e32 v[14:15], 0
	s_sub_i32 s62, 0x42, s59
	v_mov_b64_e32 v[16:17], 0
	s_min_i32 s62, s62, 8
	v_mov_b64_e32 v[18:19], 0
	s_abs_i32 s63, s62
	v_mov_b64_e32 v[20:21], 0
	v_cvt_f32_u32_e32 v0, s63
	v_mov_b64_e32 v[22:23], 0
	s_sub_i32 s84, 0, s63
	v_mov_b64_e32 v[24:25], 0
	s_mulk_i32 s58, 0xb0
	v_mov_b64_e32 v[26:27], 0
	s_sub_i32 s7, s7, s58
	v_mov_b64_e32 v[28:29], 0
	v_rcp_iflag_f32_e32 v0, v0
	v_mov_b64_e32 v[30:31], 0
	s_abs_i32 s58, s7
	v_mov_b64_e32 v[32:33], 0
	s_xor_b32 s73, s7, s62
	v_mov_b64_e32 v[34:35], 0
	s_ashr_i32 s73, s73, 31
	v_mov_b64_e32 v[36:37], 0
	v_mul_f32_e32 v0, 0x4f7ffffe, v0
	v_mov_b64_e32 v[38:39], 0
	v_cvt_u32_f32_e32 v0, v0
	v_mov_b64_e32 v[40:41], 0
	s_mov_b64 s[88:89], -1
	v_mov_b64_e32 v[42:43], 0
	v_readfirstlane_b32 s85, v0
	v_mov_b64_e32 v[44:45], 0
	s_mul_i32 s84, s84, s85
	v_mov_b64_e32 v[46:47], 0
	s_mul_hi_u32 s84, s85, s84
	v_mov_b64_e32 v[48:49], 0
	s_add_i32 s85, s85, s84
	v_mov_b64_e32 v[50:51], 0
	s_mul_hi_u32 s84, s58, s85
	v_mov_b64_e32 v[52:53], 0
	s_mul_i32 s85, s84, s63
	v_mov_b64_e32 v[54:55], 0
	s_sub_i32 s58, s58, s85
	v_mov_b64_e32 v[56:57], 0
	s_add_i32 s86, s84, 1
	v_mov_b64_e32 v[58:59], 0
	s_sub_i32 s85, s58, s63
	v_mov_b64_e32 v[60:61], 0
	s_cmp_ge_u32 s58, s63
	v_mov_b64_e32 v[62:63], 0
	s_cselect_b32 s84, s86, s84
	v_mov_b64_e32 v[64:65], 0
	s_cselect_b32 s58, s85, s58
	v_mov_b64_e32 v[66:67], 0
	s_add_i32 s85, s84, 1
	v_mov_b64_e32 v[68:69], 0
	s_cmp_ge_u32 s58, s63
	v_mov_b64_e32 v[70:71], 0
	s_cselect_b32 s58, s85, s84
	v_mov_b64_e32 v[72:73], 0
	s_xor_b32 s58, s58, s73
	v_mov_b64_e32 v[74:75], 0
	s_sub_i32 s84, s58, s73
	v_mov_b64_e32 v[76:77], 0
	s_mul_i32 s58, s84, s62
	v_mov_b64_e32 v[78:79], 0
	s_sub_i32 s7, s7, s58
	v_mov_b64_e32 v[80:81], 0
	s_add_i32 s86, s59, s7
	v_mov_b64_e32 v[82:83], 0
.LBB0_1667:
	s_ashr_i32 s87, s86, 31
	v_mov_b64_e32 v[84:85], 0
	s_lshl_b64 s[58:59], s[86:87], 19
	v_mov_b64_e32 v[86:87], 0
	s_add_u32 s90, s1, s58
	v_mov_b64_e32 v[88:89], 0
	s_addc_u32 s91, s3, s59
	v_mov_b64_e32 v[90:91], 0
	s_and_b64 s[58:59], s[88:89], exec
	v_mov_b64_e32 v[124:125], 0
	s_cselect_b32 s7, s91, s23
	v_mov_b64_e32 v[126:127], 0
	s_cselect_b32 s62, s90, s22
	v_mov_b64_e32 v[128:129], 0
	s_ashr_i32 s85, s84, 31
	v_mov_b64_e32 v[130:131], 0
	s_lshl_b64 s[58:59], s[84:85], 19
	v_mov_b64_e32 v[132:133], 0
	s_add_u32 s92, s4, s58
	v_mov_b64_e32 v[134:135], 0
	s_addc_u32 s93, s5, s59
	v_mov_b64_e32 v[136:137], 0
	s_and_b64 s[58:59], s[88:89], exec
	v_mov_b64_e32 v[138:139], 0
	s_cselect_b32 s63, s93, s9
	v_mov_b64_e32 v[140:141], 0
	s_cselect_b32 s73, s92, s8
	v_mov_b64_e32 v[142:143], 0
	s_add_u32 s85, s8, 0x100
	v_mov_b64_e32 v[144:145], 0
	s_addc_u32 s87, s9, 0
	v_mov_b64_e32 v[146:147], 0
	s_add_u32 s8, s22, 0x40080
	v_mov_b64_e32 v[148:149], 0
	s_addc_u32 s9, s23, 0
	v_mov_b64_e32 v[150:151], 0
	s_mov_b32 s94, -2
	v_mov_b64_e32 v[152:153], 0
	v_mov_b64_e32 v[154:155], 0
	v_mov_b64_e32 v[156:157], 0
	v_mov_b64_e32 v[158:159], 0
	v_mov_b64_e32 v[0:1], 0
